# RESID epilogue row chunks regenerated by hand: v_fma_mix convert+add, squares in original order, DPP folded into adds, reduction of chunk p interleaved with chunk p+1 (no hazard nops), LDS rows read o
# baseline (speedup 1.0000x reference)
; DI float h_lo(unsigned u) { return (float)__builtin_bit_cast(h2_t, u)[0]; }
; DI float h_hi(unsigned u) { return (float)__builtin_bit_cast(h2_t, u)[1]; }
; template <int EPI>
; DI void gemm_epilogue(const Ep& e, int m0, int n0) {
;     ...
;   } else if constexpr (EPI == EPI_RESID) {
; #pragma unroll
;     for (int p = 0; p < 8; ++p) {
;       const int row = p * 32 + (t >> 4), c8 = (t & 15) * 8;
;       const float4 a = *(const float4*)(T + row * 132 + c8), b = *(const float4*)(T + row * 132 + c8 + 4);
;       bf16_t* bp = e.xb + (size_t)(m0 + row) * DM + n0 + c8;
;       const uint4 xo4 = *(const uint4*)bp;
;       uint4 u;
;       u.x = pack2h(h_lo(xo4.x) + a.x, h_hi(xo4.x) + a.y); u.y = pack2h(h_lo(xo4.y) + a.z, h_hi(xo4.y) + a.w);
;       u.z = pack2h(h_lo(xo4.z) + b.x, h_hi(xo4.z) + b.y); u.w = pack2h(h_lo(xo4.w) + b.z, h_hi(xo4.w) + b.w);
;       *(uint4*)bp = u;
;       const float r0 = h_lo(u.x), r1 = h_hi(u.x), r2 = h_lo(u.y), r3 = h_hi(u.y);
;       const float r4 = h_lo(u.z), r5 = h_hi(u.z), r6 = h_lo(u.w), r7 = h_hi(u.w);
;       float s2 = r0 * r0 + r1 * r1 + r2 * r2 + r3 * r3 + r4 * r4 + r5 * r5 + r6 * r6 + r7 * r7;
;       s2 += __shfl_xor(s2, 1); s2 += __shfl_xor(s2, 2); s2 += __shfl_xor(s2, 4);
;       if ((t & 7) == 0) e.ss_out[(size_t)(m0 + row) * 16 + ((n0 + c8) >> 6)] = s2;
;     ...
;   float* T = (float*)smem;
; #pragma unroll
;   for (int bj = 0; bj < 2; ++bj) {
; #pragma unroll
;     for (int ai = 0; ai < 2; ++ai)
; #pragma unroll
;       for (int m = 0; m < 4; ++m)
; #pragma unroll
;         for (int n = 0; n < 2; ++n)
; #pragma unroll
;           for (int j = 0; j < 4; ++j)
;             T[(ai * 128 + wr * 64 + m * 16 + fq * 4 + j) * 132 + wc * 32 + n * 16 + fr] = acc[ai][bj][m][n][j];
;     __syncthreads();
.LBB0_911:
	s_or_b64 exec, exec, s[2:3]
	s_movk_i32 s2, 0x100
	v_cmp_gt_i32_e32 vcc, s2, v3
	s_waitcnt vmcnt(0)
	s_barrier
	s_and_saveexec_b64 s[2:3], vcc
	v_lshl_add_u32 v0, v3, 2, v234
	v_mov_b32_e32 v1, 1.0
	ds_write_b32 v0, v1
	s_or_b64 exec, exec, s[2:3]
	v_lshl_or_b32 v0, v148, 2, v149
	v_lshlrev_b32_e32 v1, 2, v147
	s_movk_i32 s12, 0x210
	v_lshl_or_b32 v1, v146, 7, v1
	v_mul_lo_u32 v0, v0, s12
	v_add_u32_e32 v132, v1, v0
	ds_write2_b32 v132, v104, v116 offset1:16
	ds_write2_b32 v132, v105, v117 offset0:132 offset1:148
	v_add_u32_e32 v104, 0x400, v132
	v_add_u32_e32 v105, 0x2000, v132
	ds_write2_b32 v104, v106, v118 offset0:8 offset1:24
	ds_write2_b32 v104, v107, v119 offset0:140 offset1:156
	ds_write2_b32 v105, v100, v108 offset0:64 offset1:80
	ds_write2_b32 v105, v101, v109 offset0:196 offset1:212
	v_add_u32_e32 v100, 0x2400, v132
	v_add_u32_e32 v101, 0x4000, v132
	ds_write2_b32 v100, v102, v110 offset0:72 offset1:88
	ds_write2_b32 v100, v103, v111 offset0:204 offset1:220
	ds_write2_b32 v101, v92, v96 offset0:128 offset1:144
	v_add_u32_e32 v92, 0x4400, v132
	ds_write2_b32 v92, v93, v97 offset0:4 offset1:20
	ds_write2_b32 v92, v94, v98 offset0:136 offset1:152
	v_add_u32_e32 v94, 0x6000, v132
	v_add_u32_e32 v93, 0x4800, v132
	ds_write2_b32 v94, v84, v88 offset0:192 offset1:208
	v_add_u32_e32 v84, 0x6400, v132
	v_or_b32_e32 v3, 64, v1
	ds_write2_b32 v93, v95, v99 offset0:12 offset1:28
	ds_write2_b32 v84, v85, v89 offset0:68 offset1:84
	ds_write2_b32 v84, v86, v90 offset0:200 offset1:216
	v_add_u32_e32 v85, 0x6800, v132
	v_add_u32_e32 v90, 0x10800, v0
	ds_write2_b32 v85, v87, v91 offset0:76 offset1:92
	v_add_u32_e32 v86, v1, v90
	v_add_u32_e32 v91, 0x10a10, v0
	v_add_u32_e32 v90, v3, v90
	v_add_u32_e32 v95, 0x10c20, v0
	ds_write_b32 v90, v124
	v_add_u32_e32 v90, v3, v91
	v_add_u32_e32 v96, 0x10e30, v0
	ds_write_b32 v90, v125
	v_add_u32_e32 v90, v3, v95
	ds_write_b32 v90, v126
	v_add_u32_e32 v90, v3, v96
	v_add_u32_e32 v97, 0x12900, v0
	ds_write_b32 v90, v127
	v_add_u32_e32 v90, v1, v97
	v_add_u32_e32 v98, 0x12b10, v0
	v_add_u32_e32 v97, v3, v97
	v_add_u32_e32 v99, 0x12d20, v0
	ds_write_b32 v97, v112
	v_add_u32_e32 v97, v3, v98
	v_add_u32_e32 v102, 0x12f30, v0
	ds_write_b32 v97, v113
	v_add_u32_e32 v97, v3, v99
	v_add_u32_e32 v87, v1, v91
	v_add_u32_e32 v91, v1, v98
	ds_write_b32 v97, v114
	v_add_u32_e32 v97, v3, v102
	v_add_u32_e32 v98, 0x14a00, v0
	v_add_u32_e32 v88, v1, v95
	v_add_u32_e32 v95, v1, v99
	ds_write_b32 v97, v115
	v_add_u32_e32 v97, v1, v98
	v_add_u32_e32 v99, 0x14c10, v0
	v_add_u32_e32 v89, v1, v96
	v_add_u32_e32 v96, v1, v102
	ds_write_b32 v97, v80
	v_add_u32_e32 v80, v1, v99
	v_add_u32_e32 v102, 0x14e20, v0
	ds_write_b32 v80, v81
	v_add_u32_e32 v81, v1, v102
	v_add_u32_e32 v103, 0x15030, v0
	ds_write_b32 v81, v82
	v_add_u32_e32 v82, v1, v103
	ds_write_b32 v82, v83
	v_add_u32_e32 v83, v3, v98
	ds_write_b32 v83, v76
	v_add_u32_e32 v76, v3, v99
	ds_write_b32 v76, v77
	v_add_u32_e32 v76, v3, v102
	ds_write_b32 v76, v78
	v_add_u32_e32 v76, v3, v103
	v_add_u32_e32 v83, 0x16b00, v0
	ds_write_b32 v76, v79
	v_add_u32_e32 v76, v1, v83
	ds_write_b32 v76, v72
	v_add_u32_e32 v72, 0x16d10, v0
	v_add_u32_e32 v77, v1, v72
	ds_write_b32 v77, v73
	v_add_u32_e32 v73, 0x16f20, v0
	v_add_u32_e32 v0, 0x17130, v0
	v_add_u32_e32 v78, v1, v73
	v_add_u32_e32 v79, v1, v0
	v_add_u32_e32 v1, v3, v83
	ds_write_b32 v1, v68
	v_add_u32_e32 v1, v3, v72
	ds_write_b32 v1, v69
	v_add_u32_e32 v1, v3, v73
	v_add_u32_e32 v0, v3, v0
	v_mov_b32_e32 v73, v224
	ds_write_b32 v86, v128
	ds_write_b32 v87, v129
	ds_write_b32 v88, v130
	ds_write_b32 v89, v131
	ds_write_b32 v90, v120
	ds_write_b32 v91, v121
	ds_write_b32 v95, v122
	ds_write_b32 v96, v123
	ds_write_b32 v78, v74
	ds_write_b32 v79, v75
	ds_write_b32 v1, v70
	ds_write_b32 v0, v71
	s_waitcnt lgkmcnt(0)
	s_barrier
	v_mov_b32_e32 v71, v2
	v_ashrrev_i32_e32 v72, 4, v73
	v_add_u32_e32 v68, s25, v72
	v_lshlrev_b32_e32 v0, 3, v73
	v_ashrrev_i32_e32 v69, 31, v68
	v_and_b32_e32 v99, 0x78, v0
	v_lshlrev_b64 v[0:1], 11, v[68:69]
	v_lshl_add_u64 v[0:1], s[6:7], 0, v[0:1]
	v_lshl_add_u64 v[0:1], s[8:9], 1, v[0:1]
	v_lshlrev_b32_e32 v70, 1, v99
	v_lshl_add_u64 v[102:103], v[0:1], 0, v[70:71]
	v_mov_b32_e32 v226, 0x10000
	v_mov_b32_e32 v227, 0
	global_load_dwordx4 v[156:159], v[102:103], off
	v_lshl_add_u64 v[236:237], v[102:103], 0, v[226:227]
	global_load_dwordx4 v[160:163], v[236:237], off
	v_lshl_add_u64 v[238:239], v[236:237], 0, v[226:227]
	global_load_dwordx4 v[164:167], v[238:239], off
	v_lshl_add_u64 v[240:241], v[238:239], 0, v[226:227]
	global_load_dwordx4 v[168:171], v[240:241], off
	v_lshl_add_u64 v[242:243], v[240:241], 0, v[226:227]
	global_load_dwordx4 v[172:175], v[242:243], off
	v_lshl_add_u64 v[244:245], v[242:243], 0, v[226:227]
	global_load_dwordx4 v[176:179], v[244:245], off
	v_lshl_add_u64 v[246:247], v[244:245], 0, v[226:227]
	global_load_dwordx4 v[180:183], v[246:247], off
	v_lshl_add_u64 v[248:249], v[246:247], 0, v[226:227]
	global_load_dwordx4 v[184:187], v[248:249], off
	global_load_dwordx4 v[188:191], v[102:103], off offset:256
	global_load_dwordx4 v[192:195], v[236:237], off offset:256
	global_load_dwordx4 v[196:199], v[238:239], off offset:256
	global_load_dwordx4 v[200:203], v[240:241], off offset:256
	global_load_dwordx4 v[204:207], v[242:243], off offset:256
	global_load_dwordx4 v[208:211], v[244:245], off offset:256
	global_load_dwordx4 v[212:215], v[246:247], off offset:256
	global_load_dwordx4 v[216:219], v[248:249], off offset:256
	s_add_u32 s2, s0, 0xf640000
	s_addc_u32 s3, s1, 0
	v_lshrrev_b32_e32 v220, 4, v224
	v_and_b32_e32 v221, 15, v224
	v_mul_u32_u24_e32 v98, 0x210, v220
	v_lshl_add_u32 v98, v221, 5, v98
	v_add_u32_e32 v99, 0x10800, v98
	v_and_b32_e32 v233, 7, v224
	v_cmp_eq_u32_e64 s[100:101], 0, v233
	v_lshlrev_b32_e32 v221, 3, v221
	v_or_b32_e32 v221, s8, v221
	v_ashrrev_i32_e32 v221, 6, v221
	v_add_u32_e32 v220, s25, v220
	v_lshlrev_b32_e32 v220, 6, v220
	v_lshl_add_u32 v222, v221, 2, v220
	ds_read_b128 v[106:109], v98
	ds_read_b128 v[110:113], v98 offset:16
	ds_read_b128 v[68:71], v98 offset:16896
	ds_read_b128 v[72:75], v98 offset:16912
	s_waitcnt vmcnt(15)
; DI float h_lo(unsigned u) { return (float)__builtin_bit_cast(h2_t, u)[0]; }
; DI float h_hi(unsigned u) { return (float)__builtin_bit_cast(h2_t, u)[1]; }
; template <int EPI>
; DI void gemm_epilogue(const Ep& e, int m0, int n0) {
;     ...
;   } else if constexpr (EPI == EPI_RESID) {
; #pragma unroll
;     for (int p = 0; p < 8; ++p) {
;       const int row = p * 32 + (t >> 4), c8 = (t & 15) * 8;
;       const float4 a = *(const float4*)(T + row * 132 + c8), b = *(const float4*)(T + row * 132 + c8 + 4);
;       bf16_t* bp = e.xb + (size_t)(m0 + row) * DM + n0 + c8;
;       const uint4 xo4 = *(const uint4*)bp;
;       uint4 u;
;       u.x = pack2h(h_lo(xo4.x) + a.x, h_hi(xo4.x) + a.y); u.y = pack2h(h_lo(xo4.y) + a.z, h_hi(xo4.y) + a.w);
;       u.z = pack2h(h_lo(xo4.z) + b.x, h_hi(xo4.z) + b.y); u.w = pack2h(h_lo(xo4.w) + b.z, h_hi(xo4.w) + b.w);
;       *(uint4*)bp = u;
;       const float r0 = h_lo(u.x), r1 = h_hi(u.x), r2 = h_lo(u.y), r3 = h_hi(u.y);
;       const float r4 = h_lo(u.z), r5 = h_hi(u.z), r6 = h_lo(u.w), r7 = h_hi(u.w);
;       float s2 = r0 * r0 + r1 * r1 + r2 * r2 + r3 * r3 + r4 * r4 + r5 * r5 + r6 * r6 + r7 * r7;
;       s2 += __shfl_xor(s2, 1); s2 += __shfl_xor(s2, 2); s2 += __shfl_xor(s2, 4);
;       if ((t & 7) == 0) e.ss_out[(size_t)(m0 + row) * 16 + ((n0 + c8) >> 6)] = s2;
;     }
;     return;
	s_waitcnt lgkmcnt(2)
	v_fma_mix_f32 v106, v156, 1.0, v106 op_sel_hi:[1,0,0]
	v_fma_mix_f32 v107, v156, 1.0, v107 op_sel:[1,0,0] op_sel_hi:[1,0,0]
	v_fma_mix_f32 v108, v157, 1.0, v108 op_sel_hi:[1,0,0]
	v_fma_mix_f32 v109, v157, 1.0, v109 op_sel:[1,0,0] op_sel_hi:[1,0,0]
	v_fma_mix_f32 v110, v158, 1.0, v110 op_sel_hi:[1,0,0]
	v_fma_mix_f32 v111, v158, 1.0, v111 op_sel:[1,0,0] op_sel_hi:[1,0,0]
	v_fma_mix_f32 v112, v159, 1.0, v112 op_sel_hi:[1,0,0]
	v_fma_mix_f32 v113, v159, 1.0, v113 op_sel:[1,0,0] op_sel_hi:[1,0,0]
	v_cvt_pk_f16_f32 v114, v106, v107
	v_cvt_pk_f16_f32 v115, v108, v109
	v_cvt_pk_f16_f32 v116, v110, v111
	v_cvt_pk_f16_f32 v117, v112, v113
	global_store_dwordx4 v[102:103], v[114:117], off
	ds_read_b128 v[106:109], v98 offset:33792
	ds_read_b128 v[110:113], v98 offset:33808
	s_waitcnt vmcnt(15)
	s_waitcnt lgkmcnt(2)
	v_fma_mix_f32 v68, v160, 1.0, v68 op_sel_hi:[1,0,0]
	v_fma_mix_f32 v118, v114, v114, 0 op_sel:[1,1,0] op_sel_hi:[1,1,0]
	v_fma_mix_f32 v69, v160, 1.0, v69 op_sel:[1,0,0] op_sel_hi:[1,0,0]
	v_fma_mix_f32 v118, v114, v114, v118 op_sel_hi:[1,1,0]
	v_fma_mix_f32 v70, v161, 1.0, v70 op_sel_hi:[1,0,0]
	v_fma_mix_f32 v118, v115, v115, v118 op_sel_hi:[1,1,0]
	v_fma_mix_f32 v71, v161, 1.0, v71 op_sel:[1,0,0] op_sel_hi:[1,0,0]
	v_fma_mix_f32 v118, v115, v115, v118 op_sel:[1,1,0] op_sel_hi:[1,1,0]
	v_fma_mix_f32 v72, v162, 1.0, v72 op_sel_hi:[1,0,0]
	v_fma_mix_f32 v118, v116, v116, v118 op_sel_hi:[1,1,0]
	v_fma_mix_f32 v73, v162, 1.0, v73 op_sel:[1,0,0] op_sel_hi:[1,0,0]
	v_fma_mix_f32 v118, v116, v116, v118 op_sel:[1,1,0] op_sel_hi:[1,1,0]
	v_fma_mix_f32 v74, v163, 1.0, v74 op_sel_hi:[1,0,0]
	v_fma_mix_f32 v118, v117, v117, v118 op_sel_hi:[1,1,0]
	v_fma_mix_f32 v75, v163, 1.0, v75 op_sel:[1,0,0] op_sel_hi:[1,0,0]
	v_fma_mix_f32 v118, v117, v117, v118 op_sel:[1,1,0] op_sel_hi:[1,1,0]
	v_cvt_pk_f16_f32 v228, v68, v69
	v_cvt_pk_f16_f32 v229, v70, v71
	v_add_f32_dpp v118, v118, v118 quad_perm:[1,0,3,2] row_mask:0xf bank_mask:0xf
	v_cvt_pk_f16_f32 v230, v72, v73
	v_cvt_pk_f16_f32 v231, v74, v75
	v_add_f32_dpp v118, v118, v118 quad_perm:[2,3,0,1] row_mask:0xf bank_mask:0xf
	global_store_dwordx4 v[236:237], v[228:231], off
	v_mov_b32_e32 v223, v222
	v_add_f32_dpp v3, v118, v118 row_half_mirror row_mask:0xf bank_mask:0xf
	s_and_saveexec_b64 s[0:1], s[100:101]
	global_store_dword v223, v3, s[2:3]
	s_or_b64 exec, exec, s[0:1]
	ds_read_b128 v[68:71], v98 offset:50688
	ds_read_b128 v[72:75], v98 offset:50704
	s_waitcnt vmcnt(15)
	s_waitcnt lgkmcnt(2)
	v_fma_mix_f32 v106, v164, 1.0, v106 op_sel_hi:[1,0,0]
	v_fma_mix_f32 v232, v228, v228, 0 op_sel:[1,1,0] op_sel_hi:[1,1,0]
	v_fma_mix_f32 v107, v164, 1.0, v107 op_sel:[1,0,0] op_sel_hi:[1,0,0]
	v_fma_mix_f32 v232, v228, v228, v232 op_sel_hi:[1,1,0]
	v_fma_mix_f32 v108, v165, 1.0, v108 op_sel_hi:[1,0,0]
	v_fma_mix_f32 v232, v229, v229, v232 op_sel_hi:[1,1,0]
	v_fma_mix_f32 v109, v165, 1.0, v109 op_sel:[1,0,0] op_sel_hi:[1,0,0]
	v_fma_mix_f32 v232, v229, v229, v232 op_sel:[1,1,0] op_sel_hi:[1,1,0]
	v_fma_mix_f32 v110, v166, 1.0, v110 op_sel_hi:[1,0,0]
	v_fma_mix_f32 v232, v230, v230, v232 op_sel_hi:[1,1,0]
	v_fma_mix_f32 v111, v166, 1.0, v111 op_sel:[1,0,0] op_sel_hi:[1,0,0]
	v_fma_mix_f32 v232, v230, v230, v232 op_sel:[1,1,0] op_sel_hi:[1,1,0]
	v_fma_mix_f32 v112, v167, 1.0, v112 op_sel_hi:[1,0,0]
	v_fma_mix_f32 v232, v231, v231, v232 op_sel_hi:[1,1,0]
	v_fma_mix_f32 v113, v167, 1.0, v113 op_sel:[1,0,0] op_sel_hi:[1,0,0]
	v_fma_mix_f32 v232, v231, v231, v232 op_sel:[1,1,0] op_sel_hi:[1,1,0]
	v_cvt_pk_f16_f32 v114, v106, v107
	v_cvt_pk_f16_f32 v115, v108, v109
	v_add_f32_dpp v232, v232, v232 quad_perm:[1,0,3,2] row_mask:0xf bank_mask:0xf
	v_cvt_pk_f16_f32 v116, v110, v111
	v_cvt_pk_f16_f32 v117, v112, v113
	v_add_f32_dpp v232, v232, v232 quad_perm:[2,3,0,1] row_mask:0xf bank_mask:0xf
	global_store_dwordx4 v[238:239], v[114:117], off
	v_add_u32_e32 v223, 0x800, v222
	v_add_f32_dpp v3, v232, v232 row_half_mirror row_mask:0xf bank_mask:0xf
	s_and_saveexec_b64 s[0:1], s[100:101]
	global_store_dword v223, v3, s[2:3]
	s_or_b64 exec, exec, s[0:1]
	ds_read_b128 v[106:109], v99
	ds_read_b128 v[110:113], v99 offset:16
	s_waitcnt vmcnt(15)
	s_waitcnt lgkmcnt(2)
	v_fma_mix_f32 v68, v168, 1.0, v68 op_sel_hi:[1,0,0]
	v_fma_mix_f32 v118, v114, v114, 0 op_sel:[1,1,0] op_sel_hi:[1,1,0]
	v_fma_mix_f32 v69, v168, 1.0, v69 op_sel:[1,0,0] op_sel_hi:[1,0,0]
	v_fma_mix_f32 v118, v114, v114, v118 op_sel_hi:[1,1,0]
	v_fma_mix_f32 v70, v169, 1.0, v70 op_sel_hi:[1,0,0]
	v_fma_mix_f32 v118, v115, v115, v118 op_sel_hi:[1,1,0]
	v_fma_mix_f32 v71, v169, 1.0, v71 op_sel:[1,0,0] op_sel_hi:[1,0,0]
	v_fma_mix_f32 v118, v115, v115, v118 op_sel:[1,1,0] op_sel_hi:[1,1,0]
	v_fma_mix_f32 v72, v170, 1.0, v72 op_sel_hi:[1,0,0]
	v_fma_mix_f32 v118, v116, v116, v118 op_sel_hi:[1,1,0]
	v_fma_mix_f32 v73, v170, 1.0, v73 op_sel:[1,0,0] op_sel_hi:[1,0,0]
	v_fma_mix_f32 v118, v116, v116, v118 op_sel:[1,1,0] op_sel_hi:[1,1,0]
	v_fma_mix_f32 v74, v171, 1.0, v74 op_sel_hi:[1,0,0]
	v_fma_mix_f32 v118, v117, v117, v118 op_sel_hi:[1,1,0]
	v_fma_mix_f32 v75, v171, 1.0, v75 op_sel:[1,0,0] op_sel_hi:[1,0,0]
	v_fma_mix_f32 v118, v117, v117, v118 op_sel:[1,1,0] op_sel_hi:[1,1,0]
	v_cvt_pk_f16_f32 v228, v68, v69
	v_cvt_pk_f16_f32 v229, v70, v71
	v_add_f32_dpp v118, v118, v118 quad_perm:[1,0,3,2] row_mask:0xf bank_mask:0xf
	v_cvt_pk_f16_f32 v230, v72, v73
	v_cvt_pk_f16_f32 v231, v74, v75
	v_add_f32_dpp v118, v118, v118 quad_perm:[2,3,0,1] row_mask:0xf bank_mask:0xf
	global_store_dwordx4 v[240:241], v[228:231], off
	v_add_u32_e32 v223, 0x1000, v222
	v_add_f32_dpp v3, v118, v118 row_half_mirror row_mask:0xf bank_mask:0xf
	s_and_saveexec_b64 s[0:1], s[100:101]
	global_store_dword v223, v3, s[2:3]
	s_or_b64 exec, exec, s[0:1]
	ds_read_b128 v[68:71], v99 offset:16896
	ds_read_b128 v[72:75], v99 offset:16912
	s_waitcnt vmcnt(15)
; DI float h_lo(unsigned u) { return (float)__builtin_bit_cast(h2_t, u)[0]; }
; DI float h_hi(unsigned u) { return (float)__builtin_bit_cast(h2_t, u)[1]; }
; template <int EPI>
; DI void gemm_epilogue(const Ep& e, int m0, int n0) {
;     ...
;   } else if constexpr (EPI == EPI_RESID) {
; #pragma unroll
;     for (int p = 0; p < 8; ++p) {
;       const int row = p * 32 + (t >> 4), c8 = (t & 15) * 8;
;       const float4 a = *(const float4*)(T + row * 132 + c8), b = *(const float4*)(T + row * 132 + c8 + 4);
;       bf16_t* bp = e.xb + (size_t)(m0 + row) * DM + n0 + c8;
;       const uint4 xo4 = *(const uint4*)bp;
;       uint4 u;
;       u.x = pack2h(h_lo(xo4.x) + a.x, h_hi(xo4.x) + a.y); u.y = pack2h(h_lo(xo4.y) + a.z, h_hi(xo4.y) + a.w);
;       u.z = pack2h(h_lo(xo4.z) + b.x, h_hi(xo4.z) + b.y); u.w = pack2h(h_lo(xo4.w) + b.z, h_hi(xo4.w) + b.w);
;       *(uint4*)bp = u;
;       const float r0 = h_lo(u.x), r1 = h_hi(u.x), r2 = h_lo(u.y), r3 = h_hi(u.y);
;       const float r4 = h_lo(u.z), r5 = h_hi(u.z), r6 = h_lo(u.w), r7 = h_hi(u.w);
;       float s2 = r0 * r0 + r1 * r1 + r2 * r2 + r3 * r3 + r4 * r4 + r5 * r5 + r6 * r6 + r7 * r7;
;       s2 += __shfl_xor(s2, 1); s2 += __shfl_xor(s2, 2); s2 += __shfl_xor(s2, 4);
;       if ((t & 7) == 0) e.ss_out[(size_t)(m0 + row) * 16 + ((n0 + c8) >> 6)] = s2;
;     }
;     return;
	s_waitcnt lgkmcnt(2)
	v_fma_mix_f32 v106, v172, 1.0, v106 op_sel_hi:[1,0,0]
	v_fma_mix_f32 v232, v228, v228, 0 op_sel:[1,1,0] op_sel_hi:[1,1,0]
	v_fma_mix_f32 v107, v172, 1.0, v107 op_sel:[1,0,0] op_sel_hi:[1,0,0]
	v_fma_mix_f32 v232, v228, v228, v232 op_sel_hi:[1,1,0]
	v_fma_mix_f32 v108, v173, 1.0, v108 op_sel_hi:[1,0,0]
	v_fma_mix_f32 v232, v229, v229, v232 op_sel_hi:[1,1,0]
	v_fma_mix_f32 v109, v173, 1.0, v109 op_sel:[1,0,0] op_sel_hi:[1,0,0]
	v_fma_mix_f32 v232, v229, v229, v232 op_sel:[1,1,0] op_sel_hi:[1,1,0]
	v_fma_mix_f32 v110, v174, 1.0, v110 op_sel_hi:[1,0,0]
	v_fma_mix_f32 v232, v230, v230, v232 op_sel_hi:[1,1,0]
	v_fma_mix_f32 v111, v174, 1.0, v111 op_sel:[1,0,0] op_sel_hi:[1,0,0]
	v_fma_mix_f32 v232, v230, v230, v232 op_sel:[1,1,0] op_sel_hi:[1,1,0]
	v_fma_mix_f32 v112, v175, 1.0, v112 op_sel_hi:[1,0,0]
	v_fma_mix_f32 v232, v231, v231, v232 op_sel_hi:[1,1,0]
	v_fma_mix_f32 v113, v175, 1.0, v113 op_sel:[1,0,0] op_sel_hi:[1,0,0]
	v_fma_mix_f32 v232, v231, v231, v232 op_sel:[1,1,0] op_sel_hi:[1,1,0]
	v_cvt_pk_f16_f32 v114, v106, v107
	v_cvt_pk_f16_f32 v115, v108, v109
	v_add_f32_dpp v232, v232, v232 quad_perm:[1,0,3,2] row_mask:0xf bank_mask:0xf
	v_cvt_pk_f16_f32 v116, v110, v111
	v_cvt_pk_f16_f32 v117, v112, v113
	v_add_f32_dpp v232, v232, v232 quad_perm:[2,3,0,1] row_mask:0xf bank_mask:0xf
	global_store_dwordx4 v[242:243], v[114:117], off
	v_add_u32_e32 v223, 0x1800, v222
	v_add_f32_dpp v3, v232, v232 row_half_mirror row_mask:0xf bank_mask:0xf
	s_and_saveexec_b64 s[0:1], s[100:101]
	global_store_dword v223, v3, s[2:3]
	s_or_b64 exec, exec, s[0:1]
	ds_read_b128 v[106:109], v99 offset:33792
	ds_read_b128 v[110:113], v99 offset:33808
	s_waitcnt vmcnt(15)
	s_waitcnt lgkmcnt(2)
	v_fma_mix_f32 v68, v176, 1.0, v68 op_sel_hi:[1,0,0]
	v_fma_mix_f32 v118, v114, v114, 0 op_sel:[1,1,0] op_sel_hi:[1,1,0]
	v_fma_mix_f32 v69, v176, 1.0, v69 op_sel:[1,0,0] op_sel_hi:[1,0,0]
	v_fma_mix_f32 v118, v114, v114, v118 op_sel_hi:[1,1,0]
	v_fma_mix_f32 v70, v177, 1.0, v70 op_sel_hi:[1,0,0]
	v_fma_mix_f32 v118, v115, v115, v118 op_sel_hi:[1,1,0]
	v_fma_mix_f32 v71, v177, 1.0, v71 op_sel:[1,0,0] op_sel_hi:[1,0,0]
	v_fma_mix_f32 v118, v115, v115, v118 op_sel:[1,1,0] op_sel_hi:[1,1,0]
	v_fma_mix_f32 v72, v178, 1.0, v72 op_sel_hi:[1,0,0]
	v_fma_mix_f32 v118, v116, v116, v118 op_sel_hi:[1,1,0]
	v_fma_mix_f32 v73, v178, 1.0, v73 op_sel:[1,0,0] op_sel_hi:[1,0,0]
	v_fma_mix_f32 v118, v116, v116, v118 op_sel:[1,1,0] op_sel_hi:[1,1,0]
	v_fma_mix_f32 v74, v179, 1.0, v74 op_sel_hi:[1,0,0]
	v_fma_mix_f32 v118, v117, v117, v118 op_sel_hi:[1,1,0]
	v_fma_mix_f32 v75, v179, 1.0, v75 op_sel:[1,0,0] op_sel_hi:[1,0,0]
	v_fma_mix_f32 v118, v117, v117, v118 op_sel:[1,1,0] op_sel_hi:[1,1,0]
	v_cvt_pk_f16_f32 v228, v68, v69
	v_cvt_pk_f16_f32 v229, v70, v71
	v_add_f32_dpp v118, v118, v118 quad_perm:[1,0,3,2] row_mask:0xf bank_mask:0xf
	v_cvt_pk_f16_f32 v230, v72, v73
	v_cvt_pk_f16_f32 v231, v74, v75
	v_add_f32_dpp v118, v118, v118 quad_perm:[2,3,0,1] row_mask:0xf bank_mask:0xf
	global_store_dwordx4 v[244:245], v[228:231], off
	v_add_u32_e32 v223, 0x2000, v222
	v_add_f32_dpp v3, v118, v118 row_half_mirror row_mask:0xf bank_mask:0xf
	s_and_saveexec_b64 s[0:1], s[100:101]
	global_store_dword v223, v3, s[2:3]
	s_or_b64 exec, exec, s[0:1]
	ds_read_b128 v[68:71], v99 offset:50688
	ds_read_b128 v[72:75], v99 offset:50704
	s_waitcnt vmcnt(15)
	s_waitcnt lgkmcnt(2)
	v_fma_mix_f32 v106, v180, 1.0, v106 op_sel_hi:[1,0,0]
	v_fma_mix_f32 v232, v228, v228, 0 op_sel:[1,1,0] op_sel_hi:[1,1,0]
	v_fma_mix_f32 v107, v180, 1.0, v107 op_sel:[1,0,0] op_sel_hi:[1,0,0]
	v_fma_mix_f32 v232, v228, v228, v232 op_sel_hi:[1,1,0]
	v_fma_mix_f32 v108, v181, 1.0, v108 op_sel_hi:[1,0,0]
	v_fma_mix_f32 v232, v229, v229, v232 op_sel_hi:[1,1,0]
	v_fma_mix_f32 v109, v181, 1.0, v109 op_sel:[1,0,0] op_sel_hi:[1,0,0]
	v_fma_mix_f32 v232, v229, v229, v232 op_sel:[1,1,0] op_sel_hi:[1,1,0]
	v_fma_mix_f32 v110, v182, 1.0, v110 op_sel_hi:[1,0,0]
	v_fma_mix_f32 v232, v230, v230, v232 op_sel_hi:[1,1,0]
	v_fma_mix_f32 v111, v182, 1.0, v111 op_sel:[1,0,0] op_sel_hi:[1,0,0]
	v_fma_mix_f32 v232, v230, v230, v232 op_sel:[1,1,0] op_sel_hi:[1,1,0]
	v_fma_mix_f32 v112, v183, 1.0, v112 op_sel_hi:[1,0,0]
	v_fma_mix_f32 v232, v231, v231, v232 op_sel_hi:[1,1,0]
	v_fma_mix_f32 v113, v183, 1.0, v113 op_sel:[1,0,0] op_sel_hi:[1,0,0]
	v_fma_mix_f32 v232, v231, v231, v232 op_sel:[1,1,0] op_sel_hi:[1,1,0]
	v_cvt_pk_f16_f32 v114, v106, v107
	v_cvt_pk_f16_f32 v115, v108, v109
	v_add_f32_dpp v232, v232, v232 quad_perm:[1,0,3,2] row_mask:0xf bank_mask:0xf
	v_cvt_pk_f16_f32 v116, v110, v111
	v_cvt_pk_f16_f32 v117, v112, v113
	v_add_f32_dpp v232, v232, v232 quad_perm:[2,3,0,1] row_mask:0xf bank_mask:0xf
	global_store_dwordx4 v[246:247], v[114:117], off
	v_add_u32_e32 v223, 0x2800, v222
	v_add_f32_dpp v3, v232, v232 row_half_mirror row_mask:0xf bank_mask:0xf
	s_and_saveexec_b64 s[0:1], s[100:101]
	global_store_dword v223, v3, s[2:3]
	s_or_b64 exec, exec, s[0:1]
	s_waitcnt vmcnt(15)
	s_waitcnt lgkmcnt(0)
; DI float h_lo(unsigned u) { return (float)__builtin_bit_cast(h2_t, u)[0]; }
; DI float h_hi(unsigned u) { return (float)__builtin_bit_cast(h2_t, u)[1]; }
; template <int EPI>
; DI void gemm_epilogue(const Ep& e, int m0, int n0) {
;     ...
;   } else if constexpr (EPI == EPI_RESID) {
; #pragma unroll
;     for (int p = 0; p < 8; ++p) {
;       const int row = p * 32 + (t >> 4), c8 = (t & 15) * 8;
;       const float4 a = *(const float4*)(T + row * 132 + c8), b = *(const float4*)(T + row * 132 + c8 + 4);
;       bf16_t* bp = e.xb + (size_t)(m0 + row) * DM + n0 + c8;
;       const uint4 xo4 = *(const uint4*)bp;
;       uint4 u;
;       u.x = pack2h(h_lo(xo4.x) + a.x, h_hi(xo4.x) + a.y); u.y = pack2h(h_lo(xo4.y) + a.z, h_hi(xo4.y) + a.w);
;       u.z = pack2h(h_lo(xo4.z) + b.x, h_hi(xo4.z) + b.y); u.w = pack2h(h_lo(xo4.w) + b.z, h_hi(xo4.w) + b.w);
;       *(uint4*)bp = u;
;       const float r0 = h_lo(u.x), r1 = h_hi(u.x), r2 = h_lo(u.y), r3 = h_hi(u.y);
;       const float r4 = h_lo(u.z), r5 = h_hi(u.z), r6 = h_lo(u.w), r7 = h_hi(u.w);
;       float s2 = r0 * r0 + r1 * r1 + r2 * r2 + r3 * r3 + r4 * r4 + r5 * r5 + r6 * r6 + r7 * r7;
;       s2 += __shfl_xor(s2, 1); s2 += __shfl_xor(s2, 2); s2 += __shfl_xor(s2, 4);
;       if ((t & 7) == 0) e.ss_out[(size_t)(m0 + row) * 16 + ((n0 + c8) >> 6)] = s2;
;     }
;     return;
;     ...
;   float* T = (float*)smem;
; #pragma unroll
;   for (int bj = 0; bj < 2; ++bj) {
; #pragma unroll
;     for (int ai = 0; ai < 2; ++ai)
; #pragma unroll
;       for (int m = 0; m < 4; ++m)
; #pragma unroll
;         for (int n = 0; n < 2; ++n)
; #pragma unroll
;           for (int j = 0; j < 4; ++j)
;             T[(ai * 128 + wr * 64 + m * 16 + fq * 4 + j) * 132 + wc * 32 + n * 16 + fr] = acc[ai][bj][m][n][j];
;     __syncthreads();
;     gemm_epilogue<EPI>(e, m0, n0 + bj * 128);
	v_fma_mix_f32 v68, v184, 1.0, v68 op_sel_hi:[1,0,0]
	v_fma_mix_f32 v118, v114, v114, 0 op_sel:[1,1,0] op_sel_hi:[1,1,0]
	v_fma_mix_f32 v69, v184, 1.0, v69 op_sel:[1,0,0] op_sel_hi:[1,0,0]
	v_fma_mix_f32 v118, v114, v114, v118 op_sel_hi:[1,1,0]
	v_fma_mix_f32 v70, v185, 1.0, v70 op_sel_hi:[1,0,0]
	v_fma_mix_f32 v118, v115, v115, v118 op_sel_hi:[1,1,0]
	v_fma_mix_f32 v71, v185, 1.0, v71 op_sel:[1,0,0] op_sel_hi:[1,0,0]
	v_fma_mix_f32 v118, v115, v115, v118 op_sel:[1,1,0] op_sel_hi:[1,1,0]
	v_fma_mix_f32 v72, v186, 1.0, v72 op_sel_hi:[1,0,0]
	v_fma_mix_f32 v118, v116, v116, v118 op_sel_hi:[1,1,0]
	v_fma_mix_f32 v73, v186, 1.0, v73 op_sel:[1,0,0] op_sel_hi:[1,0,0]
	v_fma_mix_f32 v118, v116, v116, v118 op_sel:[1,1,0] op_sel_hi:[1,1,0]
	v_fma_mix_f32 v74, v187, 1.0, v74 op_sel_hi:[1,0,0]
	v_fma_mix_f32 v118, v117, v117, v118 op_sel_hi:[1,1,0]
	v_fma_mix_f32 v75, v187, 1.0, v75 op_sel:[1,0,0] op_sel_hi:[1,0,0]
	v_fma_mix_f32 v118, v117, v117, v118 op_sel:[1,1,0] op_sel_hi:[1,1,0]
	v_cvt_pk_f16_f32 v228, v68, v69
	v_cvt_pk_f16_f32 v229, v70, v71
	v_add_f32_dpp v118, v118, v118 quad_perm:[1,0,3,2] row_mask:0xf bank_mask:0xf
	v_cvt_pk_f16_f32 v230, v72, v73
	v_cvt_pk_f16_f32 v231, v74, v75
	v_add_f32_dpp v118, v118, v118 quad_perm:[2,3,0,1] row_mask:0xf bank_mask:0xf
	global_store_dwordx4 v[248:249], v[228:231], off
	v_add_u32_e32 v223, 0x3000, v222
	v_add_f32_dpp v3, v118, v118 row_half_mirror row_mask:0xf bank_mask:0xf
	s_and_saveexec_b64 s[0:1], s[100:101]
	global_store_dword v223, v3, s[2:3]
	s_or_b64 exec, exec, s[0:1]
	v_fma_mix_f32 v232, v228, v228, 0 op_sel:[1,1,0] op_sel_hi:[1,1,0]
	s_nop 0
	v_fma_mix_f32 v232, v228, v228, v232 op_sel_hi:[1,1,0]
	s_nop 0
	v_fma_mix_f32 v232, v229, v229, v232 op_sel_hi:[1,1,0]
	s_nop 0
	v_fma_mix_f32 v232, v229, v229, v232 op_sel:[1,1,0] op_sel_hi:[1,1,0]
	s_nop 0
	v_fma_mix_f32 v232, v230, v230, v232 op_sel_hi:[1,1,0]
	s_nop 0
	v_fma_mix_f32 v232, v230, v230, v232 op_sel:[1,1,0] op_sel_hi:[1,1,0]
	s_nop 0
	v_fma_mix_f32 v232, v231, v231, v232 op_sel_hi:[1,1,0]
	s_nop 0
	v_fma_mix_f32 v232, v231, v231, v232 op_sel:[1,1,0] op_sel_hi:[1,1,0]
	s_nop 1
	v_add_f32_dpp v232, v232, v232 quad_perm:[1,0,3,2] row_mask:0xf bank_mask:0xf
	s_nop 1
	v_add_f32_dpp v232, v232, v232 quad_perm:[2,3,0,1] row_mask:0xf bank_mask:0xf
	v_add_u32_e32 v223, 0x3800, v222
	s_nop 0
	v_add_f32_dpp v3, v232, v232 row_half_mirror row_mask:0xf bank_mask:0xf
	s_and_saveexec_b64 s[0:1], s[100:101]
	global_store_dword v223, v3, s[2:3]
	s_or_b64 exec, exec, s[0:1]
.LBB0_929:
	s_or_b64 exec, exec, s[0:1]
	s_waitcnt lgkmcnt(0)
	s_barrier
	ds_write2_b32 v132, v4, v20 offset1:16
	ds_write2_b32 v132, v5, v21 offset0:132 offset1:148
	ds_write2_b32 v104, v6, v22 offset0:8 offset1:24
	ds_write2_b32 v104, v7, v23 offset0:140 offset1:156
	ds_write2_b32 v105, v8, v24 offset0:64 offset1:80
	ds_write2_b32 v105, v9, v25 offset0:196 offset1:212
	ds_write2_b32 v100, v10, v26 offset0:72 offset1:88
	ds_write2_b32 v100, v11, v27 offset0:204 offset1:220
	ds_write2_b32 v101, v12, v28 offset0:128 offset1:144
	ds_write2_b32 v92, v13, v29 offset0:4 offset1:20
	ds_write2_b32 v92, v14, v30 offset0:136 offset1:152
	ds_write2_b32 v93, v15, v31 offset0:12 offset1:28
	ds_write2_b32 v94, v16, v32 offset0:192 offset1:208
	ds_write2_b32 v84, v17, v33 offset0:68 offset1:84
	ds_write2_b32 v84, v18, v34 offset0:200 offset1:216
	ds_write2_b32 v85, v19, v35 offset0:76 offset1:92
	ds_write2_b32 v86, v36, v52 offset1:16
	ds_write2_b32 v87, v37, v53 offset1:16
	ds_write2_b32 v88, v38, v54 offset1:16
	ds_write2_b32 v89, v39, v55 offset1:16
	ds_write2_b32 v90, v40, v56 offset1:16
	ds_write2_b32 v91, v41, v57 offset1:16
	ds_write2_b32 v95, v42, v58 offset1:16
	ds_write2_b32 v96, v43, v59 offset1:16
	ds_write2_b32 v97, v44, v60 offset1:16
	ds_write2_b32 v80, v45, v61 offset1:16
	ds_write2_b32 v81, v46, v62 offset1:16
	ds_write2_b32 v82, v47, v63 offset1:16
	ds_write2_b32 v76, v48, v64 offset1:16
	ds_write2_b32 v77, v49, v65 offset1:16
	ds_write2_b32 v78, v50, v66 offset1:16
	ds_write2_b32 v79, v51, v67 offset1:16
	v_mov_b32_e32 v9, v224
	s_waitcnt lgkmcnt(0)
	s_barrier
	v_lshrrev_b32_e32 v220, 4, v224
	v_and_b32_e32 v221, 15, v224
	v_lshlrev_b32_e32 v221, 3, v221
	v_or_b32_e32 v221, s30, v221
	v_ashrrev_i32_e32 v221, 6, v221
	v_add_u32_e32 v220, s25, v220
	v_lshlrev_b32_e32 v220, 6, v220
	v_lshl_add_u32 v222, v221, 2, v220
	ds_read_b128 v[106:109], v98
	ds_read_b128 v[110:113], v98 offset:16
	ds_read_b128 v[68:71], v98 offset:16896
	ds_read_b128 v[72:75], v98 offset:16912
	s_waitcnt vmcnt(15)
	s_waitcnt lgkmcnt(2)
	v_fma_mix_f32 v106, v188, 1.0, v106 op_sel_hi:[1,0,0]
	v_fma_mix_f32 v107, v188, 1.0, v107 op_sel:[1,0,0] op_sel_hi:[1,0,0]
	v_fma_mix_f32 v108, v189, 1.0, v108 op_sel_hi:[1,0,0]
	v_fma_mix_f32 v109, v189, 1.0, v109 op_sel:[1,0,0] op_sel_hi:[1,0,0]
	v_fma_mix_f32 v110, v190, 1.0, v110 op_sel_hi:[1,0,0]
	v_fma_mix_f32 v111, v190, 1.0, v111 op_sel:[1,0,0] op_sel_hi:[1,0,0]
	v_fma_mix_f32 v112, v191, 1.0, v112 op_sel_hi:[1,0,0]
	v_fma_mix_f32 v113, v191, 1.0, v113 op_sel:[1,0,0] op_sel_hi:[1,0,0]
	v_cvt_pk_f16_f32 v114, v106, v107
	v_cvt_pk_f16_f32 v115, v108, v109
	v_cvt_pk_f16_f32 v116, v110, v111
	v_cvt_pk_f16_f32 v117, v112, v113
	global_store_dwordx4 v[102:103], v[114:117], off offset:256
	ds_read_b128 v[106:109], v98 offset:33792
	ds_read_b128 v[110:113], v98 offset:33808
	s_waitcnt vmcnt(15)
	s_waitcnt lgkmcnt(2)
; DI float h_lo(unsigned u) { return (float)__builtin_bit_cast(h2_t, u)[0]; }
; DI float h_hi(unsigned u) { return (float)__builtin_bit_cast(h2_t, u)[1]; }
; template <int EPI>
; DI void gemm_epilogue(const Ep& e, int m0, int n0) {
;     ...
;   } else if constexpr (EPI == EPI_RESID) {
; #pragma unroll
;     for (int p = 0; p < 8; ++p) {
;       const int row = p * 32 + (t >> 4), c8 = (t & 15) * 8;
;       const float4 a = *(const float4*)(T + row * 132 + c8), b = *(const float4*)(T + row * 132 + c8 + 4);
;       bf16_t* bp = e.xb + (size_t)(m0 + row) * DM + n0 + c8;
;       const uint4 xo4 = *(const uint4*)bp;
;       uint4 u;
;       u.x = pack2h(h_lo(xo4.x) + a.x, h_hi(xo4.x) + a.y); u.y = pack2h(h_lo(xo4.y) + a.z, h_hi(xo4.y) + a.w);
;       u.z = pack2h(h_lo(xo4.z) + b.x, h_hi(xo4.z) + b.y); u.w = pack2h(h_lo(xo4.w) + b.z, h_hi(xo4.w) + b.w);
;       *(uint4*)bp = u;
;       const float r0 = h_lo(u.x), r1 = h_hi(u.x), r2 = h_lo(u.y), r3 = h_hi(u.y);
;       const float r4 = h_lo(u.z), r5 = h_hi(u.z), r6 = h_lo(u.w), r7 = h_hi(u.w);
;       float s2 = r0 * r0 + r1 * r1 + r2 * r2 + r3 * r3 + r4 * r4 + r5 * r5 + r6 * r6 + r7 * r7;
;       s2 += __shfl_xor(s2, 1); s2 += __shfl_xor(s2, 2); s2 += __shfl_xor(s2, 4);
;       if ((t & 7) == 0) e.ss_out[(size_t)(m0 + row) * 16 + ((n0 + c8) >> 6)] = s2;
;     }
;     return;
	v_fma_mix_f32 v68, v192, 1.0, v68 op_sel_hi:[1,0,0]
	v_fma_mix_f32 v118, v114, v114, 0 op_sel:[1,1,0] op_sel_hi:[1,1,0]
	v_fma_mix_f32 v69, v192, 1.0, v69 op_sel:[1,0,0] op_sel_hi:[1,0,0]
	v_fma_mix_f32 v118, v114, v114, v118 op_sel_hi:[1,1,0]
	v_fma_mix_f32 v70, v193, 1.0, v70 op_sel_hi:[1,0,0]
	v_fma_mix_f32 v118, v115, v115, v118 op_sel_hi:[1,1,0]
	v_fma_mix_f32 v71, v193, 1.0, v71 op_sel:[1,0,0] op_sel_hi:[1,0,0]
	v_fma_mix_f32 v118, v115, v115, v118 op_sel:[1,1,0] op_sel_hi:[1,1,0]
	v_fma_mix_f32 v72, v194, 1.0, v72 op_sel_hi:[1,0,0]
	v_fma_mix_f32 v118, v116, v116, v118 op_sel_hi:[1,1,0]
	v_fma_mix_f32 v73, v194, 1.0, v73 op_sel:[1,0,0] op_sel_hi:[1,0,0]
	v_fma_mix_f32 v118, v116, v116, v118 op_sel:[1,1,0] op_sel_hi:[1,1,0]
	v_fma_mix_f32 v74, v195, 1.0, v74 op_sel_hi:[1,0,0]
	v_fma_mix_f32 v118, v117, v117, v118 op_sel_hi:[1,1,0]
	v_fma_mix_f32 v75, v195, 1.0, v75 op_sel:[1,0,0] op_sel_hi:[1,0,0]
	v_fma_mix_f32 v118, v117, v117, v118 op_sel:[1,1,0] op_sel_hi:[1,1,0]
	v_cvt_pk_f16_f32 v228, v68, v69
	v_cvt_pk_f16_f32 v229, v70, v71
	v_add_f32_dpp v118, v118, v118 quad_perm:[1,0,3,2] row_mask:0xf bank_mask:0xf
	v_cvt_pk_f16_f32 v230, v72, v73
	v_cvt_pk_f16_f32 v231, v74, v75
	v_add_f32_dpp v118, v118, v118 quad_perm:[2,3,0,1] row_mask:0xf bank_mask:0xf
	global_store_dwordx4 v[236:237], v[228:231], off offset:256
	v_mov_b32_e32 v223, v222
	v_add_f32_dpp v3, v118, v118 row_half_mirror row_mask:0xf bank_mask:0xf
	s_and_saveexec_b64 s[0:1], s[100:101]
	global_store_dword v223, v3, s[2:3]
	s_or_b64 exec, exec, s[0:1]
	ds_read_b128 v[68:71], v98 offset:50688
	ds_read_b128 v[72:75], v98 offset:50704
	s_waitcnt vmcnt(15)
	s_waitcnt lgkmcnt(2)
	v_fma_mix_f32 v106, v196, 1.0, v106 op_sel_hi:[1,0,0]
	v_fma_mix_f32 v232, v228, v228, 0 op_sel:[1,1,0] op_sel_hi:[1,1,0]
	v_fma_mix_f32 v107, v196, 1.0, v107 op_sel:[1,0,0] op_sel_hi:[1,0,0]
	v_fma_mix_f32 v232, v228, v228, v232 op_sel_hi:[1,1,0]
	v_fma_mix_f32 v108, v197, 1.0, v108 op_sel_hi:[1,0,0]
	v_fma_mix_f32 v232, v229, v229, v232 op_sel_hi:[1,1,0]
	v_fma_mix_f32 v109, v197, 1.0, v109 op_sel:[1,0,0] op_sel_hi:[1,0,0]
	v_fma_mix_f32 v232, v229, v229, v232 op_sel:[1,1,0] op_sel_hi:[1,1,0]
	v_fma_mix_f32 v110, v198, 1.0, v110 op_sel_hi:[1,0,0]
	v_fma_mix_f32 v232, v230, v230, v232 op_sel_hi:[1,1,0]
	v_fma_mix_f32 v111, v198, 1.0, v111 op_sel:[1,0,0] op_sel_hi:[1,0,0]
	v_fma_mix_f32 v232, v230, v230, v232 op_sel:[1,1,0] op_sel_hi:[1,1,0]
	v_fma_mix_f32 v112, v199, 1.0, v112 op_sel_hi:[1,0,0]
	v_fma_mix_f32 v232, v231, v231, v232 op_sel_hi:[1,1,0]
	v_fma_mix_f32 v113, v199, 1.0, v113 op_sel:[1,0,0] op_sel_hi:[1,0,0]
	v_fma_mix_f32 v232, v231, v231, v232 op_sel:[1,1,0] op_sel_hi:[1,1,0]
	v_cvt_pk_f16_f32 v114, v106, v107
	v_cvt_pk_f16_f32 v115, v108, v109
	v_add_f32_dpp v232, v232, v232 quad_perm:[1,0,3,2] row_mask:0xf bank_mask:0xf
	v_cvt_pk_f16_f32 v116, v110, v111
	v_cvt_pk_f16_f32 v117, v112, v113
	v_add_f32_dpp v232, v232, v232 quad_perm:[2,3,0,1] row_mask:0xf bank_mask:0xf
	global_store_dwordx4 v[238:239], v[114:117], off offset:256
	v_add_u32_e32 v223, 0x800, v222
	v_add_f32_dpp v3, v232, v232 row_half_mirror row_mask:0xf bank_mask:0xf
	s_and_saveexec_b64 s[0:1], s[100:101]
	global_store_dword v223, v3, s[2:3]
	s_or_b64 exec, exec, s[0:1]
	ds_read_b128 v[106:109], v99
	ds_read_b128 v[110:113], v99 offset:16
	s_waitcnt vmcnt(15)
	s_waitcnt lgkmcnt(2)
	v_fma_mix_f32 v68, v200, 1.0, v68 op_sel_hi:[1,0,0]
	v_fma_mix_f32 v118, v114, v114, 0 op_sel:[1,1,0] op_sel_hi:[1,1,0]
	v_fma_mix_f32 v69, v200, 1.0, v69 op_sel:[1,0,0] op_sel_hi:[1,0,0]
	v_fma_mix_f32 v118, v114, v114, v118 op_sel_hi:[1,1,0]
	v_fma_mix_f32 v70, v201, 1.0, v70 op_sel_hi:[1,0,0]
	v_fma_mix_f32 v118, v115, v115, v118 op_sel_hi:[1,1,0]
	v_fma_mix_f32 v71, v201, 1.0, v71 op_sel:[1,0,0] op_sel_hi:[1,0,0]
	v_fma_mix_f32 v118, v115, v115, v118 op_sel:[1,1,0] op_sel_hi:[1,1,0]
	v_fma_mix_f32 v72, v202, 1.0, v72 op_sel_hi:[1,0,0]
	v_fma_mix_f32 v118, v116, v116, v118 op_sel_hi:[1,1,0]
	v_fma_mix_f32 v73, v202, 1.0, v73 op_sel:[1,0,0] op_sel_hi:[1,0,0]
	v_fma_mix_f32 v118, v116, v116, v118 op_sel:[1,1,0] op_sel_hi:[1,1,0]
	v_fma_mix_f32 v74, v203, 1.0, v74 op_sel_hi:[1,0,0]
	v_fma_mix_f32 v118, v117, v117, v118 op_sel_hi:[1,1,0]
	v_fma_mix_f32 v75, v203, 1.0, v75 op_sel:[1,0,0] op_sel_hi:[1,0,0]
	v_fma_mix_f32 v118, v117, v117, v118 op_sel:[1,1,0] op_sel_hi:[1,1,0]
	v_cvt_pk_f16_f32 v228, v68, v69
	v_cvt_pk_f16_f32 v229, v70, v71
	v_add_f32_dpp v118, v118, v118 quad_perm:[1,0,3,2] row_mask:0xf bank_mask:0xf
	v_cvt_pk_f16_f32 v230, v72, v73
	v_cvt_pk_f16_f32 v231, v74, v75
	v_add_f32_dpp v118, v118, v118 quad_perm:[2,3,0,1] row_mask:0xf bank_mask:0xf
	global_store_dwordx4 v[240:241], v[228:231], off offset:256
	v_add_u32_e32 v223, 0x1000, v222
	v_add_f32_dpp v3, v118, v118 row_half_mirror row_mask:0xf bank_mask:0xf
	s_and_saveexec_b64 s[0:1], s[100:101]
	global_store_dword v223, v3, s[2:3]
	s_or_b64 exec, exec, s[0:1]
	ds_read_b128 v[68:71], v99 offset:16896
	ds_read_b128 v[72:75], v99 offset:16912
	s_waitcnt vmcnt(15)
	s_waitcnt lgkmcnt(2)
; DI float h_lo(unsigned u) { return (float)__builtin_bit_cast(h2_t, u)[0]; }
; DI float h_hi(unsigned u) { return (float)__builtin_bit_cast(h2_t, u)[1]; }
; template <int EPI>
; DI void gemm_epilogue(const Ep& e, int m0, int n0) {
;     ...
;   } else if constexpr (EPI == EPI_RESID) {
; #pragma unroll
;     for (int p = 0; p < 8; ++p) {
;       const int row = p * 32 + (t >> 4), c8 = (t & 15) * 8;
;       const float4 a = *(const float4*)(T + row * 132 + c8), b = *(const float4*)(T + row * 132 + c8 + 4);
;       bf16_t* bp = e.xb + (size_t)(m0 + row) * DM + n0 + c8;
;       const uint4 xo4 = *(const uint4*)bp;
;       uint4 u;
;       u.x = pack2h(h_lo(xo4.x) + a.x, h_hi(xo4.x) + a.y); u.y = pack2h(h_lo(xo4.y) + a.z, h_hi(xo4.y) + a.w);
;       u.z = pack2h(h_lo(xo4.z) + b.x, h_hi(xo4.z) + b.y); u.w = pack2h(h_lo(xo4.w) + b.z, h_hi(xo4.w) + b.w);
;       *(uint4*)bp = u;
;       const float r0 = h_lo(u.x), r1 = h_hi(u.x), r2 = h_lo(u.y), r3 = h_hi(u.y);
;       const float r4 = h_lo(u.z), r5 = h_hi(u.z), r6 = h_lo(u.w), r7 = h_hi(u.w);
;       float s2 = r0 * r0 + r1 * r1 + r2 * r2 + r3 * r3 + r4 * r4 + r5 * r5 + r6 * r6 + r7 * r7;
;       s2 += __shfl_xor(s2, 1); s2 += __shfl_xor(s2, 2); s2 += __shfl_xor(s2, 4);
;       if ((t & 7) == 0) e.ss_out[(size_t)(m0 + row) * 16 + ((n0 + c8) >> 6)] = s2;
;     }
;     return;
	v_fma_mix_f32 v106, v204, 1.0, v106 op_sel_hi:[1,0,0]
	v_fma_mix_f32 v232, v228, v228, 0 op_sel:[1,1,0] op_sel_hi:[1,1,0]
	v_fma_mix_f32 v107, v204, 1.0, v107 op_sel:[1,0,0] op_sel_hi:[1,0,0]
	v_fma_mix_f32 v232, v228, v228, v232 op_sel_hi:[1,1,0]
	v_fma_mix_f32 v108, v205, 1.0, v108 op_sel_hi:[1,0,0]
	v_fma_mix_f32 v232, v229, v229, v232 op_sel_hi:[1,1,0]
	v_fma_mix_f32 v109, v205, 1.0, v109 op_sel:[1,0,0] op_sel_hi:[1,0,0]
	v_fma_mix_f32 v232, v229, v229, v232 op_sel:[1,1,0] op_sel_hi:[1,1,0]
	v_fma_mix_f32 v110, v206, 1.0, v110 op_sel_hi:[1,0,0]
	v_fma_mix_f32 v232, v230, v230, v232 op_sel_hi:[1,1,0]
	v_fma_mix_f32 v111, v206, 1.0, v111 op_sel:[1,0,0] op_sel_hi:[1,0,0]
	v_fma_mix_f32 v232, v230, v230, v232 op_sel:[1,1,0] op_sel_hi:[1,1,0]
	v_fma_mix_f32 v112, v207, 1.0, v112 op_sel_hi:[1,0,0]
	v_fma_mix_f32 v232, v231, v231, v232 op_sel_hi:[1,1,0]
	v_fma_mix_f32 v113, v207, 1.0, v113 op_sel:[1,0,0] op_sel_hi:[1,0,0]
	v_fma_mix_f32 v232, v231, v231, v232 op_sel:[1,1,0] op_sel_hi:[1,1,0]
	v_cvt_pk_f16_f32 v114, v106, v107
	v_cvt_pk_f16_f32 v115, v108, v109
	v_add_f32_dpp v232, v232, v232 quad_perm:[1,0,3,2] row_mask:0xf bank_mask:0xf
	v_cvt_pk_f16_f32 v116, v110, v111
	v_cvt_pk_f16_f32 v117, v112, v113
	v_add_f32_dpp v232, v232, v232 quad_perm:[2,3,0,1] row_mask:0xf bank_mask:0xf
	global_store_dwordx4 v[242:243], v[114:117], off offset:256
	v_add_u32_e32 v223, 0x1800, v222
	v_add_f32_dpp v3, v232, v232 row_half_mirror row_mask:0xf bank_mask:0xf
	s_and_saveexec_b64 s[0:1], s[100:101]
	global_store_dword v223, v3, s[2:3]
	s_or_b64 exec, exec, s[0:1]
	ds_read_b128 v[106:109], v99 offset:33792
	ds_read_b128 v[110:113], v99 offset:33808
	s_waitcnt vmcnt(15)
	s_waitcnt lgkmcnt(2)
	v_fma_mix_f32 v68, v208, 1.0, v68 op_sel_hi:[1,0,0]
	v_fma_mix_f32 v118, v114, v114, 0 op_sel:[1,1,0] op_sel_hi:[1,1,0]
	v_fma_mix_f32 v69, v208, 1.0, v69 op_sel:[1,0,0] op_sel_hi:[1,0,0]
	v_fma_mix_f32 v118, v114, v114, v118 op_sel_hi:[1,1,0]
	v_fma_mix_f32 v70, v209, 1.0, v70 op_sel_hi:[1,0,0]
	v_fma_mix_f32 v118, v115, v115, v118 op_sel_hi:[1,1,0]
	v_fma_mix_f32 v71, v209, 1.0, v71 op_sel:[1,0,0] op_sel_hi:[1,0,0]
	v_fma_mix_f32 v118, v115, v115, v118 op_sel:[1,1,0] op_sel_hi:[1,1,0]
	v_fma_mix_f32 v72, v210, 1.0, v72 op_sel_hi:[1,0,0]
	v_fma_mix_f32 v118, v116, v116, v118 op_sel_hi:[1,1,0]
	v_fma_mix_f32 v73, v210, 1.0, v73 op_sel:[1,0,0] op_sel_hi:[1,0,0]
	v_fma_mix_f32 v118, v116, v116, v118 op_sel:[1,1,0] op_sel_hi:[1,1,0]
	v_fma_mix_f32 v74, v211, 1.0, v74 op_sel_hi:[1,0,0]
	v_fma_mix_f32 v118, v117, v117, v118 op_sel_hi:[1,1,0]
	v_fma_mix_f32 v75, v211, 1.0, v75 op_sel:[1,0,0] op_sel_hi:[1,0,0]
	v_fma_mix_f32 v118, v117, v117, v118 op_sel:[1,1,0] op_sel_hi:[1,1,0]
	v_cvt_pk_f16_f32 v228, v68, v69
	v_cvt_pk_f16_f32 v229, v70, v71
	v_add_f32_dpp v118, v118, v118 quad_perm:[1,0,3,2] row_mask:0xf bank_mask:0xf
	v_cvt_pk_f16_f32 v230, v72, v73
	v_cvt_pk_f16_f32 v231, v74, v75
	v_add_f32_dpp v118, v118, v118 quad_perm:[2,3,0,1] row_mask:0xf bank_mask:0xf
	global_store_dwordx4 v[244:245], v[228:231], off offset:256
	v_add_u32_e32 v223, 0x2000, v222
	v_add_f32_dpp v3, v118, v118 row_half_mirror row_mask:0xf bank_mask:0xf
	s_and_saveexec_b64 s[0:1], s[100:101]
	global_store_dword v223, v3, s[2:3]
	s_or_b64 exec, exec, s[0:1]
	ds_read_b128 v[68:71], v99 offset:50688
	ds_read_b128 v[72:75], v99 offset:50704
	s_waitcnt vmcnt(15)
	s_waitcnt lgkmcnt(2)
; DI float h_lo(unsigned u) { return (float)__builtin_bit_cast(h2_t, u)[0]; }
; DI float h_hi(unsigned u) { return (float)__builtin_bit_cast(h2_t, u)[1]; }
; template <int EPI>
; DI void gemm_epilogue(const Ep& e, int m0, int n0) {
;     ...
;   } else if constexpr (EPI == EPI_RESID) {
; #pragma unroll
;     for (int p = 0; p < 8; ++p) {
;       const int row = p * 32 + (t >> 4), c8 = (t & 15) * 8;
;       const float4 a = *(const float4*)(T + row * 132 + c8), b = *(const float4*)(T + row * 132 + c8 + 4);
;       bf16_t* bp = e.xb + (size_t)(m0 + row) * DM + n0 + c8;
;       const uint4 xo4 = *(const uint4*)bp;
;       uint4 u;
;       u.x = pack2h(h_lo(xo4.x) + a.x, h_hi(xo4.x) + a.y); u.y = pack2h(h_lo(xo4.y) + a.z, h_hi(xo4.y) + a.w);
;       u.z = pack2h(h_lo(xo4.z) + b.x, h_hi(xo4.z) + b.y); u.w = pack2h(h_lo(xo4.w) + b.z, h_hi(xo4.w) + b.w);
;       *(uint4*)bp = u;
;       const float r0 = h_lo(u.x), r1 = h_hi(u.x), r2 = h_lo(u.y), r3 = h_hi(u.y);
;       const float r4 = h_lo(u.z), r5 = h_hi(u.z), r6 = h_lo(u.w), r7 = h_hi(u.w);
;       float s2 = r0 * r0 + r1 * r1 + r2 * r2 + r3 * r3 + r4 * r4 + r5 * r5 + r6 * r6 + r7 * r7;
;       s2 += __shfl_xor(s2, 1); s2 += __shfl_xor(s2, 2); s2 += __shfl_xor(s2, 4);
;       if ((t & 7) == 0) e.ss_out[(size_t)(m0 + row) * 16 + ((n0 + c8) >> 6)] = s2;
;     }
;     return;
	v_fma_mix_f32 v106, v212, 1.0, v106 op_sel_hi:[1,0,0]
	v_fma_mix_f32 v232, v228, v228, 0 op_sel:[1,1,0] op_sel_hi:[1,1,0]
	v_fma_mix_f32 v107, v212, 1.0, v107 op_sel:[1,0,0] op_sel_hi:[1,0,0]
	v_fma_mix_f32 v232, v228, v228, v232 op_sel_hi:[1,1,0]
	v_fma_mix_f32 v108, v213, 1.0, v108 op_sel_hi:[1,0,0]
	v_fma_mix_f32 v232, v229, v229, v232 op_sel_hi:[1,1,0]
	v_fma_mix_f32 v109, v213, 1.0, v109 op_sel:[1,0,0] op_sel_hi:[1,0,0]
	v_fma_mix_f32 v232, v229, v229, v232 op_sel:[1,1,0] op_sel_hi:[1,1,0]
	v_fma_mix_f32 v110, v214, 1.0, v110 op_sel_hi:[1,0,0]
	v_fma_mix_f32 v232, v230, v230, v232 op_sel_hi:[1,1,0]
	v_fma_mix_f32 v111, v214, 1.0, v111 op_sel:[1,0,0] op_sel_hi:[1,0,0]
	v_fma_mix_f32 v232, v230, v230, v232 op_sel:[1,1,0] op_sel_hi:[1,1,0]
	v_fma_mix_f32 v112, v215, 1.0, v112 op_sel_hi:[1,0,0]
	v_fma_mix_f32 v232, v231, v231, v232 op_sel_hi:[1,1,0]
	v_fma_mix_f32 v113, v215, 1.0, v113 op_sel:[1,0,0] op_sel_hi:[1,0,0]
	v_fma_mix_f32 v232, v231, v231, v232 op_sel:[1,1,0] op_sel_hi:[1,1,0]
	v_cvt_pk_f16_f32 v114, v106, v107
	v_cvt_pk_f16_f32 v115, v108, v109
	v_add_f32_dpp v232, v232, v232 quad_perm:[1,0,3,2] row_mask:0xf bank_mask:0xf
	v_cvt_pk_f16_f32 v116, v110, v111
	v_cvt_pk_f16_f32 v117, v112, v113
	v_add_f32_dpp v232, v232, v232 quad_perm:[2,3,0,1] row_mask:0xf bank_mask:0xf
	global_store_dwordx4 v[246:247], v[114:117], off offset:256
	v_add_u32_e32 v223, 0x2800, v222
	v_add_f32_dpp v3, v232, v232 row_half_mirror row_mask:0xf bank_mask:0xf
	s_and_saveexec_b64 s[0:1], s[100:101]
	global_store_dword v223, v3, s[2:3]
	s_or_b64 exec, exec, s[0:1]
	s_waitcnt vmcnt(15)
	s_waitcnt lgkmcnt(0)
	v_fma_mix_f32 v68, v216, 1.0, v68 op_sel_hi:[1,0,0]
	v_fma_mix_f32 v118, v114, v114, 0 op_sel:[1,1,0] op_sel_hi:[1,1,0]
	v_fma_mix_f32 v69, v216, 1.0, v69 op_sel:[1,0,0] op_sel_hi:[1,0,0]
	v_fma_mix_f32 v118, v114, v114, v118 op_sel_hi:[1,1,0]
	v_fma_mix_f32 v70, v217, 1.0, v70 op_sel_hi:[1,0,0]
	v_fma_mix_f32 v118, v115, v115, v118 op_sel_hi:[1,1,0]
	v_fma_mix_f32 v71, v217, 1.0, v71 op_sel:[1,0,0] op_sel_hi:[1,0,0]
	v_fma_mix_f32 v118, v115, v115, v118 op_sel:[1,1,0] op_sel_hi:[1,1,0]
	v_fma_mix_f32 v72, v218, 1.0, v72 op_sel_hi:[1,0,0]
	v_fma_mix_f32 v118, v116, v116, v118 op_sel_hi:[1,1,0]
	v_fma_mix_f32 v73, v218, 1.0, v73 op_sel:[1,0,0] op_sel_hi:[1,0,0]
	v_fma_mix_f32 v118, v116, v116, v118 op_sel:[1,1,0] op_sel_hi:[1,1,0]
	v_fma_mix_f32 v74, v219, 1.0, v74 op_sel_hi:[1,0,0]
	v_fma_mix_f32 v118, v117, v117, v118 op_sel_hi:[1,1,0]
	v_fma_mix_f32 v75, v219, 1.0, v75 op_sel:[1,0,0] op_sel_hi:[1,0,0]
	v_fma_mix_f32 v118, v117, v117, v118 op_sel:[1,1,0] op_sel_hi:[1,1,0]
	v_cvt_pk_f16_f32 v228, v68, v69
	v_cvt_pk_f16_f32 v229, v70, v71
	v_add_f32_dpp v118, v118, v118 quad_perm:[1,0,3,2] row_mask:0xf bank_mask:0xf
	v_cvt_pk_f16_f32 v230, v72, v73
	v_cvt_pk_f16_f32 v231, v74, v75
	v_add_f32_dpp v118, v118, v118 quad_perm:[2,3,0,1] row_mask:0xf bank_mask:0xf
	global_store_dwordx4 v[248:249], v[228:231], off offset:256
	v_add_u32_e32 v223, 0x3000, v222
	v_add_f32_dpp v3, v118, v118 row_half_mirror row_mask:0xf bank_mask:0xf
	s_and_saveexec_b64 s[0:1], s[100:101]
	global_store_dword v223, v3, s[2:3]
	s_or_b64 exec, exec, s[0:1]
	v_fma_mix_f32 v232, v228, v228, 0 op_sel:[1,1,0] op_sel_hi:[1,1,0]
	s_nop 0
	v_fma_mix_f32 v232, v228, v228, v232 op_sel_hi:[1,1,0]
	s_nop 0
	v_fma_mix_f32 v232, v229, v229, v232 op_sel_hi:[1,1,0]
	s_nop 0
	v_fma_mix_f32 v232, v229, v229, v232 op_sel:[1,1,0] op_sel_hi:[1,1,0]
	s_nop 0
	v_fma_mix_f32 v232, v230, v230, v232 op_sel_hi:[1,1,0]
	s_nop 0
	v_fma_mix_f32 v232, v230, v230, v232 op_sel:[1,1,0] op_sel_hi:[1,1,0]
	s_nop 0
	v_fma_mix_f32 v232, v231, v231, v232 op_sel_hi:[1,1,0]
	s_nop 0
	v_fma_mix_f32 v232, v231, v231, v232 op_sel:[1,1,0] op_sel_hi:[1,1,0]
	s_nop 1
	v_add_f32_dpp v232, v232, v232 quad_perm:[1,0,3,2] row_mask:0xf bank_mask:0xf
	s_nop 1
	v_add_f32_dpp v232, v232, v232 quad_perm:[2,3,0,1] row_mask:0xf bank_mask:0xf
	v_add_u32_e32 v223, 0x3800, v222
	s_nop 0
	v_add_f32_dpp v3, v232, v232 row_half_mirror row_mask:0xf bank_mask:0xf
	s_and_saveexec_b64 s[0:1], s[100:101]
	global_store_dword v223, v3, s[2:3]
	s_or_b64 exec, exec, s[0:1]
	s_branch .LBB0_904
